# P4c plus layer-0 attention: hand-scheduled unmasked fast path for full tiles (batched bias-LUT reads, in-place exp, no tail-mask work), Q-load wait hoisted out of the tile loop
# speedup vs baseline: 1.0041x; 1.0041x over previous
; #define LAS __attribute__((address_space(3)))
; __device__ __forceinline__ int crow(int i, int hi) { return (i & 3) + 8 * (i >> 2) + 4 * hi; }
; #define MFMA32(a, b, c) __builtin_amdgcn_mfma_f32_32x32x16_bf16((a), (b), (c), 0, 0, 0)
; template <int DQ, bool BIAS>
; __device__ __forceinline__ void attn_item_l0(const AttnItem& A, LAS unsigned char* lds, int wave_s_) {
;     ...
;         if (t >= wlo && t <= whi) {
;             LAS unsigned char* kb = lds + buf * OKBUF; LAS unsigned char* vb = lds + 2 * OKBUF + buf * OVBUF;
;             f32x16 s[2][2];
; #pragma unroll
;             for (int kbk = 0; kbk < 2; ++kbk) {
; #pragma unroll
;                 for (int qb = 0; qb < 2; ++qb)
; #pragma unroll
;                     for (int i = 0; i < 16; ++i) s[kbk][qb][i] = 0.f;
; #pragma unroll
;                 for (int kk = 0; kk < NKK; ++kk) {
;                     const bf16x8 kf = *(const LAS bf16x8*)(kb + ((32 * kbk + r32) * OKSTR + 16 * kk + 8 * hi) * 2);
;                     s[kbk][0] = MFMA32(kf, qf[0][kk], s[kbk][0]);
;                     s[kbk][1] = MFMA32(kf, qf[1][kk], s[kbk][1]);
;                 }
;             }
; #pragma unroll
;             for (int qb = 0; qb < 2; ++qb) {
;                 const int qk = A.q_kidx0 + 64 * w + 32 * qb + r32;
;                 float mx = -3.0e38f;
; #pragma unroll
;                 for (int kbk = 0; kbk < 2; ++kbk)
; #pragma unroll
;                     for (int i = 0; i < 16; ++i) {
;                         const int kidx = 64 * t + 32 * kbk + crow(i, hi);
;                         float v = s[kbk][qb][i] * A.scale2;
;                         if (BIAS) v += lut[kidx - qk + LUT0];
;                         if (kidx >= A.nkeys) v = -1.0e30f;
;                         s[kbk][qb][i] = v; mx = fmaxf(mx, v);
;                     }
.LBB0_1038:
	s_cmp_lt_u32 s91, s70
	s_cselect_b64 s[4:5], -1, 0
	s_cmp_gt_i32 s91, s71
	s_cselect_b64 s[6:7], -1, 0
	s_or_b64 s[4:5], s[4:5], s[6:7]
	s_and_b64 vcc, exec, s[4:5]
	s_cbranch_vccnz .LBB0_1040
	s_lshl_b32 s4, s91, 6
	s_add_i32 s4, s4, 64
	s_cmp_le_u32 s4, s2
	s_cbranch_scc1 .La0_fast
	s_mul_i32 s4, s72, 0x3400
	v_add3_u32 v176, v247, s4, v249
	ds_read_b128 v[64:67], v176
	ds_read_b128 v[68:71], v176 offset:32
	s_mov_b32 s3, 0xff61b1e6
	v_subrev_u32_e32 v187, 49, v252
	v_cmp_gt_u32_e64 s[14:15], s2, v187
	s_waitcnt lgkmcnt(1)
	v_mfma_f32_32x32x16_bf16 v[112:127], v[64:67], v[132:135], 0
	ds_read_b128 v[180:183], v176 offset:6688
	v_subrev_u32_e32 v187, 48, v252
	v_cmp_gt_u32_e64 s[18:19], s2, v187
	v_subrev_u32_e32 v187, 43, v252
	v_cmp_gt_u32_e64 s[16:17], s2, v187
	v_subrev_u32_e32 v187, 42, v252
	v_cmp_gt_u32_e64 s[20:21], s2, v187
	s_nop 0
	v_mfma_f32_32x32x16_bf16 v[80:95], v[64:67], v[152:155], 0
	ds_read_b128 v[64:67], v176 offset:64
	v_subrev_u32_e32 v187, 41, v252
	v_cmp_gt_u32_e64 s[22:23], s2, v187
	v_subrev_u32_e32 v187, 40, v252
	v_cmp_gt_u32_e64 s[24:25], s2, v187
	v_subrev_u32_e32 v187, 35, v252
	v_cmp_gt_u32_e64 s[26:27], s2, v187
	s_waitcnt lgkmcnt(2)
	v_mfma_f32_32x32x16_bf16 v[112:127], v[68:71], v[136:139], v[112:127]
	v_subrev_u32_e32 v187, 34, v252
	v_cmp_gt_u32_e64 s[28:29], s2, v187
	v_subrev_u32_e32 v187, 33, v252
	v_cmp_gt_u32_e64 s[30:31], s2, v187
	v_subrev_u32_e32 v187, 32, v252
	v_cmp_gt_u32_e64 s[34:35], s2, v187
	v_subrev_u32_e32 v189, 27, v252
	s_nop 0
	v_mfma_f32_32x32x16_bf16 v[80:95], v[68:71], v[156:159], v[80:95]
	v_cmp_gt_u32_e64 s[36:37], s2, v189
	v_subrev_u32_e32 v189, 25, v252
	v_cmp_gt_u32_e64 s[40:41], s2, v189
	v_cmp_gt_u32_e64 s[66:67], s2, v252
	ds_read2_b32 v[210:211], v251 offset0:48 offset1:49
	ds_read2_b32 v[238:239], v251 offset1:1
	ds_read2_b32 v[212:213], v251 offset0:50 offset1:51
	s_waitcnt lgkmcnt(3)
	v_mfma_f32_32x32x16_bf16 v[112:127], v[64:67], v[140:143], v[112:127]
	ds_read2_b32 v[214:215], v251 offset0:56 offset1:57
	ds_read2_b32 v[216:217], v251 offset0:58 offset1:59
	s_nop 0
	v_mfma_f32_32x32x16_bf16 v[80:95], v[64:67], v[160:163], v[80:95]
	ds_read_b128 v[64:67], v176 offset:96
	s_waitcnt lgkmcnt(0)
	v_mfma_f32_32x32x16_bf16 v[112:127], v[64:67], v[144:147], v[112:127]
	s_nop 0
	v_mfma_f32_32x32x16_bf16 v[80:95], v[64:67], v[164:167], v[80:95]
	ds_read_b128 v[64:67], v176 offset:6656
	s_nop 8
	v_fmamk_f32 v120, v120, 0x3e38aa3b, v210
	v_fmamk_f32 v121, v121, 0x3e38aa3b, v211
	v_cndmask_b32_e64 v120, v243, v120, s[16:17]
	v_cndmask_b32_e64 v121, v243, v121, s[20:21]
	v_fmamk_f32 v122, v122, 0x3e38aa3b, v212
	v_fmamk_f32 v123, v123, 0x3e38aa3b, v213
	s_waitcnt lgkmcnt(0)
	v_mfma_f32_32x32x16_bf16 v[96:111], v[64:67], v[132:135], 0
	v_cndmask_b32_e64 v122, v243, v122, s[22:23]
	v_cndmask_b32_e64 v123, v243, v123, s[24:25]
	v_fmamk_f32 v124, v124, 0x3e38aa3b, v214
	v_fmamk_f32 v125, v125, 0x3e38aa3b, v215
	v_cndmask_b32_e64 v124, v243, v124, s[26:27]
	v_cndmask_b32_e64 v125, v243, v125, s[28:29]
	v_fmamk_f32 v80, v80, 0x3e38aa3b, v238
	v_mfma_f32_32x32x16_bf16 v[64:79], v[64:67], v[152:155], 0
	v_fmac_f32_e32 v239, 0x3e38aa3b, v81
	v_fmamk_f32 v126, v126, 0x3e38aa3b, v216
	v_fmamk_f32 v127, v127, 0x3e38aa3b, v217
	v_cndmask_b32_e64 v126, v243, v126, s[30:31]
	v_cndmask_b32_e64 v127, v243, v127, s[34:35]
	v_mfma_f32_32x32x16_bf16 v[96:111], v[180:183], v[136:139], v[96:111]
	v_mfma_f32_32x32x16_bf16 v[64:79], v[180:183], v[156:159], v[64:79]
	ds_read_b128 v[180:183], v176 offset:6720
	s_waitcnt lgkmcnt(0)
	v_mfma_f32_32x32x16_bf16 v[96:111], v[180:183], v[140:143], v[96:111]
	v_mfma_f32_32x32x16_bf16 v[64:79], v[180:183], v[160:163], v[64:79]
	ds_read_b128 v[180:183], v176 offset:6752
	ds_read2_b32 v[176:177], v251 offset0:32 offset1:33
	s_waitcnt lgkmcnt(0)
	v_fmamk_f32 v112, v112, 0x3e38aa3b, v176
	v_mfma_f32_32x32x16_bf16 v[96:111], v[180:183], v[144:147], v[96:111]
	v_fmamk_f32 v113, v113, 0x3e38aa3b, v177
	v_mfma_f32_32x32x16_bf16 v[64:79], v[180:183], v[164:167], v[64:79]
	v_subrev_u32_e32 v180, 59, v252
	v_cmp_gt_u32_e32 vcc, s2, v180
	v_subrev_u32_e32 v183, 57, v252
	v_cmp_gt_u32_e64 s[4:5], s2, v183
	v_cndmask_b32_e32 v180, v243, v112, vcc
	v_subrev_u32_e32 v112, 58, v252
	v_cmp_gt_u32_e64 s[6:7], s2, v112
	v_subrev_u32_e32 v183, 51, v252
	v_cmp_gt_u32_e64 s[8:9], s2, v183
	v_cndmask_b32_e64 v181, v243, v113, s[6:7]
	ds_read2_b32 v[112:113], v251 offset0:34 offset1:35
	v_subrev_u32_e32 v183, 50, v252
	v_max3_f32 v182, v180, s3, v181
	v_cmp_gt_u32_e64 s[12:13], s2, v183
	v_fmamk_f32 v64, v64, 0x3e38aa3b, v176
	s_waitcnt lgkmcnt(0)
	v_fmamk_f32 v114, v114, 0x3e38aa3b, v112
	v_cndmask_b32_e64 v184, v243, v114, s[4:5]
	v_subrev_u32_e32 v114, 56, v252
	v_fmamk_f32 v115, v115, 0x3e38aa3b, v113
	v_cmp_gt_u32_e64 s[10:11], s2, v114
	v_fmac_f32_e32 v177, 0x3e38aa3b, v65
	v_fmamk_f32 v65, v66, 0x3e38aa3b, v112
	v_cndmask_b32_e64 v185, v243, v115, s[10:11]
	ds_read2_b32 v[114:115], v251 offset0:40 offset1:41
	v_max3_f32 v182, v182, v184, v185
	v_fmac_f32_e32 v113, 0x3e38aa3b, v67
	v_fmac_f32_e32 v211, 0x3e38aa3b, v73
	v_fmac_f32_e32 v213, 0x3e38aa3b, v75
	s_waitcnt lgkmcnt(0)
	v_fmamk_f32 v116, v116, 0x3e38aa3b, v114
	v_fmamk_f32 v117, v117, 0x3e38aa3b, v115
	v_cndmask_b32_e64 v116, v243, v116, s[8:9]
	v_cndmask_b32_e64 v117, v243, v117, s[12:13]
	v_max3_f32 v186, v182, v116, v117
	ds_read2_b32 v[182:183], v251 offset0:42 offset1:43
	v_fmac_f32_e32 v115, 0x3e38aa3b, v69
	v_fmac_f32_e32 v215, 0x3e38aa3b, v77
	v_fmac_f32_e32 v217, 0x3e38aa3b, v79
	v_cndmask_b32_e64 v79, v243, v217, s[66:67]
	s_waitcnt lgkmcnt(0)
; __device__ __forceinline__ float shx(float v, int lane, int o) { return __builtin_bit_cast(float, __builtin_amdgcn_ds_bpermute((lane ^ o) << 2, __builtin_bit_cast(int, v))); }
; __device__ __forceinline__ int crow(int i, int hi) { return (i & 3) + 8 * (i >> 2) + 4 * hi; }
; template <int DQ, bool BIAS>
; __device__ __forceinline__ void attn_item_l0(const AttnItem& A, LAS unsigned char* lds, int wave_s_) {
;     ...
;             for (int qb = 0; qb < 2; ++qb) {
;                 const int qk = A.q_kidx0 + 64 * w + 32 * qb + r32;
;                 float mx = -3.0e38f;
; #pragma unroll
;                 for (int kbk = 0; kbk < 2; ++kbk)
; #pragma unroll
;                     for (int i = 0; i < 16; ++i) {
;                         const int kidx = 64 * t + 32 * kbk + crow(i, hi);
;                         float v = s[kbk][qb][i] * A.scale2;
;                         if (BIAS) v += lut[kidx - qk + LUT0];
;                         if (kidx >= A.nkeys) v = -1.0e30f;
;                         s[kbk][qb][i] = v; mx = fmaxf(mx, v);
;                     }
;                 mx = fmaxf(mx, shx(mx, lane, 32));
;                 const float mnew = fmaxf(mrun[qb], mx), alpha = __builtin_amdgcn_exp2f(mrun[qb] - mnew);
;                 mrun[qb] = mnew;
;                 float ls = 0.f;
; #pragma unroll
;                 for (int kbk = 0; kbk < 2; ++kbk)
; #pragma unroll
;                     for (int i = 0; i < 16; ++i) { const float p = __builtin_amdgcn_exp2f(s[kbk][qb][i] - mnew); s[kbk][qb][i] = p; ls += p; }
	v_fmamk_f32 v118, v118, 0x3e38aa3b, v182
	v_fmamk_f32 v119, v119, 0x3e38aa3b, v183
	v_cndmask_b32_e64 v118, v243, v118, s[14:15]
	v_cndmask_b32_e64 v119, v243, v119, s[18:19]
	v_max3_f32 v186, v186, v118, v119
	v_max3_f32 v186, v186, v120, v121
	v_max3_f32 v186, v186, v122, v123
	v_max3_f32 v186, v186, v124, v125
	v_max3_f32 v188, v186, v126, v127
	ds_read2_b32 v[186:187], v251 offset0:64 offset1:65
	v_fmac_f32_e32 v183, 0x3e38aa3b, v71
	s_waitcnt lgkmcnt(0)
	v_fmamk_f32 v96, v96, 0x3e38aa3b, v186
	v_subrev_u32_e32 v186, 26, v252
	v_fmac_f32_e32 v187, 0x3e38aa3b, v97
	v_cmp_gt_u32_e64 s[38:39], s2, v186
	v_cndmask_b32_e64 v96, v243, v96, s[36:37]
	s_nop 0
	v_cndmask_b32_e64 v97, v243, v187, s[38:39]
	ds_read2_b32 v[186:187], v251 offset0:66 offset1:67
	v_max3_f32 v188, v188, v96, v97
	s_waitcnt lgkmcnt(0)
	v_fmamk_f32 v98, v98, 0x3e38aa3b, v186
	v_cndmask_b32_e64 v189, v243, v98, s[40:41]
	v_subrev_u32_e32 v98, 24, v252
	v_fmac_f32_e32 v187, 0x3e38aa3b, v99
	v_cmp_gt_u32_e64 s[42:43], s2, v98
	ds_read2_b32 v[98:99], v251 offset0:72 offset1:73
	s_waitcnt lgkmcnt(0)
	v_fmamk_f32 v98, v100, 0x3e38aa3b, v98
	v_cndmask_b32_e64 v187, v243, v187, s[42:43]
	v_max3_f32 v186, v188, v189, v187
	v_subrev_u32_e32 v188, 19, v252
	v_cmp_gt_u32_e64 s[44:45], s2, v188
	v_fmac_f32_e32 v99, 0x3e38aa3b, v101
	v_subrev_u32_e32 v188, 17, v252
	v_cndmask_b32_e64 v100, v243, v98, s[44:45]
	v_subrev_u32_e32 v98, 18, v252
	v_cmp_gt_u32_e64 s[46:47], s2, v98
	v_cmp_gt_u32_e64 s[48:49], s2, v188
	v_add_u32_e32 v188, -11, v252
	v_cndmask_b32_e64 v101, v243, v99, s[46:47]
	ds_read2_b32 v[98:99], v251 offset0:74 offset1:75
	v_cmp_gt_u32_e64 s[52:53], s2, v188
	v_add_u32_e32 v188, -9, v252
	v_cmp_gt_u32_e64 s[56:57], s2, v188
	v_add_u32_e32 v188, -3, v252
	s_waitcnt lgkmcnt(0)
	v_fmamk_f32 v98, v102, 0x3e38aa3b, v98
	v_cndmask_b32_e64 v102, v243, v98, s[48:49]
	v_add_u32_e32 v98, -16, v252
	v_fmac_f32_e32 v99, 0x3e38aa3b, v103
	v_cmp_gt_u32_e64 s[50:51], s2, v98
	v_cmp_gt_u32_e64 s[60:61], s2, v188
	v_max3_f32 v186, v186, v100, v101
	v_cndmask_b32_e64 v103, v243, v99, s[50:51]
	ds_read2_b32 v[98:99], v251 offset0:80 offset1:81
	v_max3_f32 v186, v186, v102, v103
	v_add_u32_e32 v188, -1, v252
	v_cmp_gt_u32_e64 s[64:65], s2, v188
	v_cndmask_b32_e64 v67, v243, v113, s[42:43]
	s_waitcnt lgkmcnt(0)
	v_fmamk_f32 v98, v104, 0x3e38aa3b, v98
	v_cndmask_b32_e64 v104, v243, v98, s[52:53]
	v_add_u32_e32 v98, -10, v252
	v_fmac_f32_e32 v99, 0x3e38aa3b, v105
	v_cmp_gt_u32_e64 s[54:55], s2, v98
	v_cndmask_b32_e64 v69, v243, v115, s[46:47]
	v_cndmask_b32_e64 v71, v243, v183, s[50:51]
	v_cndmask_b32_e64 v105, v243, v99, s[54:55]
	ds_read2_b32 v[98:99], v251 offset0:82 offset1:83
	v_max3_f32 v186, v186, v104, v105
	v_cndmask_b32_e64 v73, v243, v211, s[54:55]
	s_waitcnt lgkmcnt(0)
	v_fmamk_f32 v98, v106, 0x3e38aa3b, v98
	v_cndmask_b32_e64 v106, v243, v98, s[56:57]
	v_add_u32_e32 v98, -8, v252
	v_fmac_f32_e32 v99, 0x3e38aa3b, v107
	v_cmp_gt_u32_e64 s[58:59], s2, v98
	s_nop 1
	v_cndmask_b32_e64 v107, v243, v99, s[58:59]
	ds_read2_b32 v[98:99], v251 offset0:88 offset1:89
	v_max3_f32 v186, v186, v106, v107
	v_cndmask_b32_e64 v75, v243, v213, s[58:59]
	s_waitcnt lgkmcnt(0)
	v_fmamk_f32 v98, v108, 0x3e38aa3b, v98
	v_cndmask_b32_e64 v108, v243, v98, s[60:61]
	v_add_u32_e32 v98, -2, v252
	v_fmac_f32_e32 v99, 0x3e38aa3b, v109
	v_cmp_gt_u32_e64 s[62:63], s2, v98
	s_nop 1
	v_cndmask_b32_e64 v109, v243, v99, s[62:63]
	ds_read2_b32 v[98:99], v251 offset0:90 offset1:91
	v_max3_f32 v186, v186, v108, v109
	v_cndmask_b32_e64 v77, v243, v215, s[62:63]
	s_waitcnt lgkmcnt(0)
	v_fmamk_f32 v98, v110, 0x3e38aa3b, v98
	v_fmac_f32_e32 v99, 0x3e38aa3b, v111
	v_cndmask_b32_e64 v110, v243, v98, s[64:65]
	v_cndmask_b32_e64 v99, v243, v99, s[66:67]
	v_max3_f32 v98, v186, v110, v99
	ds_bpermute_b32 v111, v173, v98
	s_movk_i32 s67, 0x1fff
	s_waitcnt lgkmcnt(0)
	v_max3_f32 v196, v178, v98, v111
	v_sub_f32_e32 v98, v180, v196
	v_exp_f32_e32 v218, v98
	v_sub_f32_e32 v98, v181, v196
	v_exp_f32_e32 v220, v98
	v_sub_f32_e32 v98, v184, v196
	v_exp_f32_e32 v222, v98
	v_sub_f32_e32 v98, v185, v196
	v_exp_f32_e32 v224, v98
	v_sub_f32_e32 v98, v116, v196
	v_exp_f32_e32 v226, v98
	v_sub_f32_e32 v98, v117, v196
	v_exp_f32_e32 v228, v98
	v_sub_f32_e32 v98, v118, v196
	v_exp_f32_e32 v230, v98
	v_sub_f32_e32 v98, v119, v196
	v_exp_f32_e32 v232, v98
	v_sub_f32_e32 v98, v120, v196
	v_exp_f32_e32 v184, v98
	v_sub_f32_e32 v98, v121, v196
	v_exp_f32_e32 v186, v98
	v_sub_f32_e32 v98, v122, v196
	v_exp_f32_e32 v188, v98
	v_sub_f32_e32 v98, v123, v196
	v_sub_f32_e32 v96, v96, v196
	v_exp_f32_e32 v190, v98
	v_sub_f32_e32 v98, v124, v196
	v_exp_f32_e32 v116, v96
	v_sub_f32_e32 v96, v97, v196
	v_exp_f32_e32 v192, v98
	v_sub_f32_e32 v98, v125, v196
	v_exp_f32_e32 v118, v96
	v_sub_f32_e32 v96, v189, v196
	v_exp_f32_e32 v194, v98
	v_sub_f32_e32 v98, v126, v196
	v_exp_f32_e32 v120, v96
	v_sub_f32_e32 v96, v187, v196
	v_exp_f32_e32 v206, v98
	v_sub_f32_e32 v98, v127, v196
	v_exp_f32_e32 v122, v96
	v_sub_f32_e32 v96, v100, v196
	v_sub_f32_e32 v97, v105, v196
	v_exp_f32_e32 v208, v98
	v_exp_f32_e32 v124, v96
	v_sub_f32_e32 v96, v101, v196
	v_exp_f32_e32 v98, v97
	v_sub_f32_e32 v97, v106, v196
	v_exp_f32_e32 v126, v96
	v_sub_f32_e32 v96, v102, v196
	v_exp_f32_e32 v100, v97
	v_sub_f32_e32 v97, v107, v196
	v_sub_f32_e32 v111, v178, v196
	v_exp_f32_e32 v178, v96
	v_sub_f32_e32 v96, v103, v196
	v_exp_f32_e32 v102, v97
	v_sub_f32_e32 v97, v108, v196
	v_exp_f32_e32 v180, v96
	v_sub_f32_e32 v96, v104, v196
	v_exp_f32_e32 v104, v97
	v_sub_f32_e32 v97, v109, v196
	v_exp_f32_e32 v106, v97
	v_sub_f32_e32 v97, v110, v196
	v_exp_f32_e32 v108, v97
	v_sub_f32_e32 v97, v99, v196
	v_exp_f32_e32 v110, v97
	v_cndmask_b32_e32 v97, v243, v80, vcc
	ds_read2_b32 v[80:81], v251 offset0:2 offset1:3
	v_cndmask_b32_e64 v99, v243, v239, s[6:7]
	v_max3_f32 v101, v97, s3, v99
	v_exp_f32_e32 v96, v96
	v_exp_f32_e32 v234, v111
	s_waitcnt lgkmcnt(0)
; __device__ __forceinline__ float shx(float v, int lane, int o) { return __builtin_bit_cast(float, __builtin_amdgcn_ds_bpermute((lane ^ o) << 2, __builtin_bit_cast(int, v))); }
; __device__ __forceinline__ int crow(int i, int hi) { return (i & 3) + 8 * (i >> 2) + 4 * hi; }
; template <int DQ, bool BIAS>
; __device__ __forceinline__ void attn_item_l0(const AttnItem& A, LAS unsigned char* lds, int wave_s_) {
;     ...
;             for (int qb = 0; qb < 2; ++qb) {
;                 const int qk = A.q_kidx0 + 64 * w + 32 * qb + r32;
;                 float mx = -3.0e38f;
; #pragma unroll
;                 for (int kbk = 0; kbk < 2; ++kbk)
; #pragma unroll
;                     for (int i = 0; i < 16; ++i) {
;                         const int kidx = 64 * t + 32 * kbk + crow(i, hi);
;                         float v = s[kbk][qb][i] * A.scale2;
;                         if (BIAS) v += lut[kidx - qk + LUT0];
;                         if (kidx >= A.nkeys) v = -1.0e30f;
;                         s[kbk][qb][i] = v; mx = fmaxf(mx, v);
;                     }
;                 mx = fmaxf(mx, shx(mx, lane, 32));
;                 const float mnew = fmaxf(mrun[qb], mx), alpha = __builtin_amdgcn_exp2f(mrun[qb] - mnew);
;                 mrun[qb] = mnew;
;                 float ls = 0.f;
; #pragma unroll
;                 for (int kbk = 0; kbk < 2; ++kbk)
; #pragma unroll
;                     for (int i = 0; i < 16; ++i) { const float p = __builtin_amdgcn_exp2f(s[kbk][qb][i] - mnew); s[kbk][qb][i] = p; ls += p; }
;                 lrun[qb] = lrun[qb] * alpha + ls;
; #pragma unroll
;                 for (int d = 0; d < 2; ++d)
; #pragma unroll
;                     for (int i = 0; i < 16; ++i) o[d][qb][i] *= alpha;
	v_fmamk_f32 v80, v82, 0x3e38aa3b, v80
	v_fmac_f32_e32 v81, 0x3e38aa3b, v83
	v_cndmask_b32_e64 v82, v243, v80, s[4:5]
	v_cndmask_b32_e64 v83, v243, v81, s[10:11]
	ds_read2_b32 v[80:81], v251 offset0:8 offset1:9
	v_max3_f32 v101, v101, v82, v83
	v_pk_mul_f32 v[46:47], v[46:47], v[234:235] op_sel_hi:[1,0]
	v_pk_mul_f32 v[44:45], v[44:45], v[234:235] op_sel_hi:[1,0]
	v_pk_mul_f32 v[42:43], v[42:43], v[234:235] op_sel_hi:[1,0]
	s_waitcnt lgkmcnt(0)
	v_fmamk_f32 v80, v84, 0x3e38aa3b, v80
	v_fmac_f32_e32 v81, 0x3e38aa3b, v85
	v_cndmask_b32_e64 v84, v243, v80, s[8:9]
	v_cndmask_b32_e64 v85, v243, v81, s[12:13]
	ds_read2_b32 v[80:81], v251 offset0:10 offset1:11
	v_max3_f32 v101, v101, v84, v85
	v_pk_mul_f32 v[40:41], v[40:41], v[234:235] op_sel_hi:[1,0]
	v_pk_mul_f32 v[38:39], v[38:39], v[234:235] op_sel_hi:[1,0]
	v_pk_mul_f32 v[36:37], v[36:37], v[234:235] op_sel_hi:[1,0]
	s_waitcnt lgkmcnt(0)
	v_fmamk_f32 v80, v86, 0x3e38aa3b, v80
	v_fmac_f32_e32 v81, 0x3e38aa3b, v87
	v_cndmask_b32_e64 v86, v243, v80, s[14:15]
	v_cndmask_b32_e64 v87, v243, v81, s[18:19]
	ds_read2_b32 v[80:81], v251 offset0:16 offset1:17
	v_max3_f32 v101, v101, v86, v87
	v_pk_mul_f32 v[34:35], v[34:35], v[234:235] op_sel_hi:[1,0]
	v_pk_mul_f32 v[32:33], v[32:33], v[234:235] op_sel_hi:[1,0]
	v_pk_mul_f32 v[62:63], v[62:63], v[234:235] op_sel_hi:[1,0]
	s_waitcnt lgkmcnt(0)
	v_fmamk_f32 v80, v88, 0x3e38aa3b, v80
	v_fmac_f32_e32 v81, 0x3e38aa3b, v89
	v_cndmask_b32_e64 v88, v243, v80, s[16:17]
	v_cndmask_b32_e64 v89, v243, v81, s[20:21]
	ds_read2_b32 v[80:81], v251 offset0:18 offset1:19
	v_max3_f32 v101, v101, v88, v89
	v_pk_mul_f32 v[60:61], v[60:61], v[234:235] op_sel_hi:[1,0]
	v_pk_mul_f32 v[58:59], v[58:59], v[234:235] op_sel_hi:[1,0]
	v_pk_mul_f32 v[56:57], v[56:57], v[234:235] op_sel_hi:[1,0]
	s_waitcnt lgkmcnt(0)
	v_fmamk_f32 v80, v90, 0x3e38aa3b, v80
	v_fmac_f32_e32 v81, 0x3e38aa3b, v91
	v_cndmask_b32_e64 v90, v243, v80, s[22:23]
	v_cndmask_b32_e64 v91, v243, v81, s[24:25]
	ds_read2_b32 v[80:81], v251 offset0:24 offset1:25
	v_max3_f32 v101, v101, v90, v91
	v_pk_mul_f32 v[54:55], v[54:55], v[234:235] op_sel_hi:[1,0]
	v_pk_mul_f32 v[52:53], v[52:53], v[234:235] op_sel_hi:[1,0]
	v_pk_mul_f32 v[50:51], v[50:51], v[234:235] op_sel_hi:[1,0]
	s_waitcnt lgkmcnt(0)
	v_fmamk_f32 v80, v92, 0x3e38aa3b, v80
	v_fmac_f32_e32 v81, 0x3e38aa3b, v93
	v_cndmask_b32_e64 v92, v243, v80, s[26:27]
	v_cndmask_b32_e64 v93, v243, v81, s[28:29]
	ds_read2_b32 v[80:81], v251 offset0:26 offset1:27
	v_max3_f32 v101, v101, v92, v93
	v_pk_mul_f32 v[48:49], v[48:49], v[234:235] op_sel_hi:[1,0]
	s_mul_i32 s4, s72, 0x2200
	s_movk_i32 s3, 0x420
	s_waitcnt lgkmcnt(0)
	v_fmamk_f32 v80, v94, 0x3e38aa3b, v80
	v_fmac_f32_e32 v81, 0x3e38aa3b, v95
	v_cndmask_b32_e64 v80, v243, v80, s[30:31]
	v_cndmask_b32_e64 v81, v243, v81, s[34:35]
	v_max3_f32 v94, v101, v80, v81
	v_cndmask_b32_e64 v95, v243, v64, s[36:37]
	v_cndmask_b32_e64 v101, v243, v177, s[38:39]
	v_max3_f32 v64, v94, v95, v101
	v_cndmask_b32_e64 v94, v243, v65, s[40:41]
	v_fmamk_f32 v65, v68, 0x3e38aa3b, v114
	v_max3_f32 v64, v64, v94, v67
	v_cndmask_b32_e64 v68, v243, v65, s[44:45]
	v_fmamk_f32 v65, v70, 0x3e38aa3b, v182
	v_max3_f32 v64, v64, v68, v69
	v_cndmask_b32_e64 v70, v243, v65, s[48:49]
	v_fmamk_f32 v65, v72, 0x3e38aa3b, v210
	v_max3_f32 v64, v64, v70, v71
	v_cndmask_b32_e64 v72, v243, v65, s[52:53]
	v_fmamk_f32 v65, v74, 0x3e38aa3b, v212
	v_max3_f32 v64, v64, v72, v73
	v_cndmask_b32_e64 v74, v243, v65, s[56:57]
	v_fmamk_f32 v65, v76, 0x3e38aa3b, v214
	v_max3_f32 v64, v64, v74, v75
	v_cndmask_b32_e64 v76, v243, v65, s[60:61]
	v_fmamk_f32 v65, v78, 0x3e38aa3b, v216
	v_max3_f32 v64, v64, v76, v77
	v_cndmask_b32_e64 v78, v243, v65, s[64:65]
	v_max3_f32 v64, v64, v78, v79
	ds_bpermute_b32 v65, v173, v64
	s_waitcnt lgkmcnt(0)
	v_max3_f32 v66, v179, v64, v65
	v_sub_f32_e32 v64, v97, v66
	v_exp_f32_e32 v219, v64
	v_sub_f32_e32 v97, v99, v66
	v_exp_f32_e32 v221, v97
	v_sub_f32_e32 v82, v82, v66
	v_exp_f32_e32 v223, v82
	v_sub_f32_e32 v82, v83, v66
	v_exp_f32_e32 v225, v82
	v_sub_f32_e32 v82, v84, v66
	v_pk_add_f32 v[64:65], v[218:219], 0 op_sel_hi:[1,0]
	v_exp_f32_e32 v227, v82
	v_sub_f32_e32 v82, v85, v66
	v_exp_f32_e32 v229, v82
	v_sub_f32_e32 v82, v86, v66
	v_pk_add_f32 v[64:65], v[220:221], v[64:65]
	v_exp_f32_e32 v231, v82
	v_sub_f32_e32 v82, v87, v66
	v_pk_add_f32 v[64:65], v[222:223], v[64:65]
	v_exp_f32_e32 v233, v82
	v_sub_f32_e32 v82, v88, v66
	v_pk_add_f32 v[64:65], v[224:225], v[64:65]
	v_exp_f32_e32 v185, v82
	v_sub_f32_e32 v82, v89, v66
	v_pk_add_f32 v[64:65], v[226:227], v[64:65]
	v_exp_f32_e32 v187, v82
	v_sub_f32_e32 v82, v90, v66
	v_pk_add_f32 v[64:65], v[228:229], v[64:65]
	v_exp_f32_e32 v189, v82
	v_sub_f32_e32 v82, v91, v66
	v_pk_add_f32 v[64:65], v[230:231], v[64:65]
	v_exp_f32_e32 v191, v82
	v_pk_add_f32 v[64:65], v[232:233], v[64:65]
	v_sub_f32_e32 v82, v92, v66
	v_pk_add_f32 v[64:65], v[184:185], v[64:65]
	v_exp_f32_e32 v193, v82
	v_sub_f32_e32 v82, v93, v66
	v_pk_add_f32 v[64:65], v[186:187], v[64:65]
	v_exp_f32_e32 v195, v82
	v_sub_f32_e32 v80, v80, v66
	v_pk_add_f32 v[64:65], v[188:189], v[64:65]
	v_exp_f32_e32 v207, v80
	v_sub_f32_e32 v80, v81, v66
	v_pk_add_f32 v[64:65], v[190:191], v[64:65]
	v_exp_f32_e32 v209, v80
	v_sub_f32_e32 v80, v95, v66
	v_exp_f32_e32 v117, v80
	v_sub_f32_e32 v80, v101, v66
	v_pk_add_f32 v[64:65], v[192:193], v[64:65]
	v_exp_f32_e32 v119, v80
	v_sub_f32_e32 v80, v94, v66
	v_pk_add_f32 v[64:65], v[194:195], v[64:65]
	v_exp_f32_e32 v121, v80
	v_sub_f32_e32 v67, v67, v66
	v_pk_add_f32 v[64:65], v[206:207], v[64:65]
	v_exp_f32_e32 v123, v67
	v_sub_f32_e32 v67, v68, v66
	v_pk_add_f32 v[64:65], v[208:209], v[64:65]
; #define LAS __attribute__((address_space(3)))
; __device__ __forceinline__ unsigned pk2c(float lo, float hi) { f32x2_t v = {lo, hi}; bf16x2_t b = __builtin_convertvector(v, bf16x2_t); return __builtin_bit_cast(unsigned, b); }
; #define MFMA32(a, b, c) __builtin_amdgcn_mfma_f32_32x32x16_bf16((a), (b), (c), 0, 0, 0)
; template <int DQ, bool BIAS>
; __device__ __forceinline__ void attn_item_l0(const AttnItem& A, LAS unsigned char* lds, int wave_s_) {
;     ...
;                 const float mnew = fmaxf(mrun[qb], mx), alpha = __builtin_amdgcn_exp2f(mrun[qb] - mnew);
;                 mrun[qb] = mnew;
;                 float ls = 0.f;
; #pragma unroll
;                 for (int kbk = 0; kbk < 2; ++kbk)
; #pragma unroll
;                     for (int i = 0; i < 16; ++i) { const float p = __builtin_amdgcn_exp2f(s[kbk][qb][i] - mnew); s[kbk][qb][i] = p; ls += p; }
;                 lrun[qb] = lrun[qb] * alpha + ls;
; #pragma unroll
;                 for (int d = 0; d < 2; ++d)
; #pragma unroll
;                     for (int i = 0; i < 16; ++i) o[d][qb][i] *= alpha;
;             }
; #pragma unroll
;             for (int kbk = 0; kbk < 2; ++kbk)
; #pragma unroll
;                 for (int st = 0; st < 2; ++st) {
;                     bf16x8 pf[2];
; #pragma unroll
;                     for (int qb = 0; qb < 2; ++qb) { u32x4 pw;
; #pragma unroll
;                         for (int j = 0; j < 4; ++j) pw[j] = pk2c(s[kbk][qb][8 * st + 2 * j], s[kbk][qb][8 * st + 2 * j + 1]);
;                         pf[qb] = __builtin_bit_cast(bf16x8, pw); }
; #pragma unroll
;                     for (int d = 0; d < 2; ++d) {
;                         const LAS unsigned char* vp = vb + ((32 * d + r32) * OVSTR + 32 * kbk + 16 * st + 4 * hi) * 2;
;                         const s16x4 lo4 = *(const LAS s16x4*)vp, hi4 = *(const LAS s16x4*)(vp + 16);
;                         const bf16x8 vf = __builtin_shufflevector(lo4, hi4, 0, 1, 2, 3, 4, 5, 6, 7);
;                         o[d][0] = MFMA32(vf, pf[0], o[d][0]);
;                         o[d][1] = MFMA32(vf, pf[1], o[d][1]);
;                     }
;                 }
	v_exp_f32_e32 v125, v67
	v_sub_f32_e32 v67, v69, v66
	v_pk_add_f32 v[64:65], v[116:117], v[64:65]
	v_exp_f32_e32 v127, v67
	v_sub_f32_e32 v67, v70, v66
	v_pk_add_f32 v[64:65], v[118:119], v[64:65]
	v_sub_f32_e32 v112, v179, v66
	v_exp_f32_e32 v179, v67
	v_pk_add_f32 v[64:65], v[120:121], v[64:65]
	v_sub_f32_e32 v67, v71, v66
	v_pk_add_f32 v[64:65], v[122:123], v[64:65]
	v_exp_f32_e32 v181, v67
	v_sub_f32_e32 v67, v72, v66
	v_pk_add_f32 v[64:65], v[124:125], v[64:65]
	v_exp_f32_e32 v97, v67
	v_sub_f32_e32 v67, v73, v66
	v_pk_add_f32 v[64:65], v[126:127], v[64:65]
	v_exp_f32_e32 v99, v67
	v_sub_f32_e32 v67, v74, v66
	v_pk_add_f32 v[64:65], v[178:179], v[64:65]
	v_exp_f32_e32 v101, v67
	v_sub_f32_e32 v67, v75, v66
	v_exp_f32_e32 v103, v67
	v_sub_f32_e32 v67, v76, v66
	v_pk_add_f32 v[64:65], v[180:181], v[64:65]
	v_exp_f32_e32 v105, v67
	v_sub_f32_e32 v67, v77, v66
	v_pk_add_f32 v[64:65], v[96:97], v[64:65]
	v_exp_f32_e32 v107, v67
	v_sub_f32_e32 v67, v78, v66
	v_pk_add_f32 v[64:65], v[98:99], v[64:65]
	v_exp_f32_e32 v109, v67
	v_sub_f32_e32 v67, v79, v66
	v_pk_add_f32 v[64:65], v[100:101], v[64:65]
	v_exp_f32_e32 v111, v67
	v_pk_add_f32 v[64:65], v[102:103], v[64:65]
	v_exp_f32_e32 v235, v112
	v_pk_add_f32 v[64:65], v[104:105], v[64:65]
	v_cvt_pk_bf16_f32 v68, v218, v220
	v_pk_add_f32 v[64:65], v[106:107], v[64:65]
	v_cvt_pk_bf16_f32 v69, v222, v224
	v_pk_add_f32 v[64:65], v[108:109], v[64:65]
	v_cvt_pk_bf16_f32 v70, v226, v228
	v_pk_add_f32 v[64:65], v[110:111], v[64:65]
	v_cvt_pk_bf16_f32 v71, v230, v232
	v_pk_fma_f32 v[168:169], v[168:169], v[234:235], v[64:65]
	v_mov_b32_e32 v64, v235
	v_pk_mul_f32 v[30:31], v[30:31], v[64:65] op_sel_hi:[1,0]
	v_pk_mul_f32 v[28:29], v[28:29], v[64:65] op_sel_hi:[1,0]
	v_pk_mul_f32 v[26:27], v[26:27], v[64:65] op_sel_hi:[1,0]
	v_pk_mul_f32 v[24:25], v[24:25], v[64:65] op_sel_hi:[1,0]
	v_pk_mul_f32 v[22:23], v[22:23], v[64:65] op_sel_hi:[1,0]
	v_pk_mul_f32 v[20:21], v[20:21], v[64:65] op_sel_hi:[1,0]
	v_pk_mul_f32 v[18:19], v[18:19], v[64:65] op_sel_hi:[1,0]
	v_pk_mul_f32 v[16:17], v[16:17], v[64:65] op_sel_hi:[1,0]
	v_pk_mul_f32 v[14:15], v[14:15], v[64:65] op_sel_hi:[1,0]
	v_pk_mul_f32 v[12:13], v[12:13], v[64:65] op_sel_hi:[1,0]
	v_pk_mul_f32 v[10:11], v[10:11], v[64:65] op_sel_hi:[1,0]
	v_pk_mul_f32 v[8:9], v[8:9], v[64:65] op_sel_hi:[1,0]
	v_pk_mul_f32 v[6:7], v[6:7], v[64:65] op_sel_hi:[1,0]
	v_pk_mul_f32 v[4:5], v[4:5], v[64:65] op_sel_hi:[1,0]
	v_pk_mul_f32 v[2:3], v[2:3], v[64:65] op_sel_hi:[1,0]
	v_pk_mul_f32 v[0:1], v[0:1], v[64:65] op_sel_hi:[1,0]
	v_add3_u32 v65, v248, s4, v250
	v_add_u32_e32 v64, 0x6800, v65
	ds_read2_b64 v[76:79], v64 offset1:2
	ds_read2_b64 v[80:83], v64 offset0:4 offset1:6
	v_cvt_pk_bf16_f32 v72, v219, v221
	v_cvt_pk_bf16_f32 v73, v223, v225
	v_cvt_pk_bf16_f32 v74, v227, v229
	v_cvt_pk_bf16_f32 v75, v231, v233
	v_add_u32_e32 v65, 0x7800, v65
	s_waitcnt lgkmcnt(1)
	v_mfma_f32_32x32x16_bf16 v[32:47], v[76:79], v[68:71], v[32:47]
	v_mfma_f32_32x32x16_bf16 v[16:31], v[76:79], v[72:75], v[16:31]
	ds_read2_b64 v[76:79], v65 offset0:32 offset1:34
	s_waitcnt lgkmcnt(0)
	v_mfma_f32_32x32x16_bf16 v[48:63], v[76:79], v[68:71], v[48:63]
	v_cvt_pk_bf16_f32 v68, v184, v186
	v_cvt_pk_bf16_f32 v69, v188, v190
	v_cvt_pk_bf16_f32 v70, v192, v194
	v_cvt_pk_bf16_f32 v71, v206, v208
	v_mfma_f32_32x32x16_bf16 v[0:15], v[76:79], v[72:75], v[0:15]
	ds_read2_b64 v[76:79], v65 offset0:36 offset1:38
	v_cvt_pk_bf16_f32 v72, v185, v187
	v_cvt_pk_bf16_f32 v73, v189, v191
	v_cvt_pk_bf16_f32 v74, v193, v195
	v_cvt_pk_bf16_f32 v75, v207, v209
	s_waitcnt lgkmcnt(0)
	v_mfma_f32_32x32x16_bf16 v[48:63], v[76:79], v[68:71], v[48:63]
	v_mfma_f32_32x32x16_bf16 v[0:15], v[76:79], v[72:75], v[0:15]
	ds_read2_b64 v[76:79], v64 offset0:8 offset1:10
	v_mfma_f32_32x32x16_bf16 v[32:47], v[80:83], v[68:71], v[32:47]
	v_cvt_pk_bf16_f32 v68, v116, v118
	v_cvt_pk_bf16_f32 v69, v120, v122
	v_cvt_pk_bf16_f32 v70, v124, v126
	v_cvt_pk_bf16_f32 v71, v178, v180
	v_mov_b32_e32 v178, v196
	v_mfma_f32_32x32x16_bf16 v[16:31], v[80:83], v[72:75], v[16:31]
	v_cvt_pk_bf16_f32 v72, v117, v119
	v_cvt_pk_bf16_f32 v73, v121, v123
	v_cvt_pk_bf16_f32 v74, v125, v127
	v_cvt_pk_bf16_f32 v75, v179, v181
	v_mov_b32_e32 v179, v66
	s_waitcnt lgkmcnt(0)
	v_mfma_f32_32x32x16_bf16 v[32:47], v[76:79], v[68:71], v[32:47]
	v_mfma_f32_32x32x16_bf16 v[16:31], v[76:79], v[72:75], v[16:31]
	ds_read2_b64 v[76:79], v65 offset0:40 offset1:42
	s_waitcnt lgkmcnt(0)
	v_mfma_f32_32x32x16_bf16 v[48:63], v[76:79], v[68:71], v[48:63]
	v_cvt_pk_bf16_f32 v68, v96, v98
	v_cvt_pk_bf16_f32 v69, v100, v102
	v_cvt_pk_bf16_f32 v70, v104, v106
	v_cvt_pk_bf16_f32 v71, v108, v110
	v_mfma_f32_32x32x16_bf16 v[0:15], v[76:79], v[72:75], v[0:15]
	ds_read2_b64 v[76:79], v64 offset0:12 offset1:14
	v_cvt_pk_bf16_f32 v72, v97, v99
	v_cvt_pk_bf16_f32 v73, v101, v103
	v_cvt_pk_bf16_f32 v74, v105, v107
	v_cvt_pk_bf16_f32 v75, v109, v111
	s_waitcnt lgkmcnt(0)
	v_mfma_f32_32x32x16_bf16 v[32:47], v[76:79], v[68:71], v[32:47]
	v_mfma_f32_32x32x16_bf16 v[16:31], v[76:79], v[72:75], v[16:31]
	ds_read2_b64 v[76:79], v65 offset0:44 offset1:46
	s_waitcnt lgkmcnt(0)
	v_mfma_f32_32x32x16_bf16 v[48:63], v[76:79], v[68:71], v[48:63]
	v_mfma_f32_32x32x16_bf16 v[0:15], v[76:79], v[72:75], v[0:15]
	s_branch .LBB0_1040
; #define LAS __attribute__((address_space(3)))
; __device__ __forceinline__ float shx(float v, int lane, int o) { return __builtin_bit_cast(float, __builtin_amdgcn_ds_bpermute((lane ^ o) << 2, __builtin_bit_cast(int, v))); }
; __device__ __forceinline__ int crow(int i, int hi) { return (i & 3) + 8 * (i >> 2) + 4 * hi; }
; #define MFMA32(a, b, c) __builtin_amdgcn_mfma_f32_32x32x16_bf16((a), (b), (c), 0, 0, 0)
; template <int DQ, bool BIAS>
; __device__ __forceinline__ void attn_item_l0(const AttnItem& A, LAS unsigned char* lds, int wave_s_) {
;     ...
;             LAS unsigned char* kb = lds + buf * OKBUF; LAS unsigned char* vb = lds + 2 * OKBUF + buf * OVBUF;
;             f32x16 s[2][2];
; #pragma unroll
;             for (int kbk = 0; kbk < 2; ++kbk) {
; #pragma unroll
;                 for (int qb = 0; qb < 2; ++qb)
; #pragma unroll
;                     for (int i = 0; i < 16; ++i) s[kbk][qb][i] = 0.f;
; #pragma unroll
;                 for (int kk = 0; kk < NKK; ++kk) {
;                     const bf16x8 kf = *(const LAS bf16x8*)(kb + ((32 * kbk + r32) * OKSTR + 16 * kk + 8 * hi) * 2);
;                     s[kbk][0] = MFMA32(kf, qf[0][kk], s[kbk][0]);
;                     s[kbk][1] = MFMA32(kf, qf[1][kk], s[kbk][1]);
;                 }
;             }
; #pragma unroll
;             for (int qb = 0; qb < 2; ++qb) {
;                 const int qk = A.q_kidx0 + 64 * w + 32 * qb + r32;
;                 float mx = -3.0e38f;
; #pragma unroll
;                 for (int kbk = 0; kbk < 2; ++kbk)
; #pragma unroll
;                     for (int i = 0; i < 16; ++i) {
;                         const int kidx = 64 * t + 32 * kbk + crow(i, hi);
;                         float v = s[kbk][qb][i] * A.scale2;
;                         if (BIAS) v += lut[kidx - qk + LUT0];
;                         if (kidx >= A.nkeys) v = -1.0e30f;
;                         s[kbk][qb][i] = v; mx = fmaxf(mx, v);
;                     }
;                 mx = fmaxf(mx, shx(mx, lane, 32));
.La0_fast:
	s_mul_i32 s4, s72, 0x3400
	v_add3_u32 v176, v247, s4, v249
	ds_read_b128 v[180:183], v176 offset:0
	ds_read_b128 v[184:187], v176 offset:32
	ds_read_b128 v[188:191], v176 offset:64
	ds_read_b128 v[192:195], v176 offset:96
	ds_read2_b32 v[206:207], v251 offset0:32 offset1:33
	ds_read2_b32 v[208:209], v251 offset0:34 offset1:35
	ds_read2_b32 v[210:211], v251 offset0:40 offset1:41
	ds_read2_b32 v[212:213], v251 offset0:42 offset1:43
	ds_read2_b32 v[214:215], v251 offset0:48 offset1:49
	ds_read2_b32 v[216:217], v251 offset0:50 offset1:51
	ds_read2_b32 v[218:219], v251 offset0:56 offset1:57
	ds_read2_b32 v[220:221], v251 offset0:58 offset1:59
	s_mul_i32 s4, s72, 0x2200
	v_add3_u32 v244, v248, s4, v250
	v_add_u32_e32 v253, 0x7800, v244
	v_add_u32_e32 v244, 0x6800, v244
	s_waitcnt lgkmcnt(11)
	v_mfma_f32_32x32x16_bf16 v[112:127], v[180:183], v[132:135], 0
	v_mfma_f32_32x32x16_bf16 v[80:95], v[180:183], v[152:155], 0
	ds_read_b128 v[180:183], v176 offset:6656
	s_waitcnt lgkmcnt(11)
	v_mfma_f32_32x32x16_bf16 v[112:127], v[184:187], v[136:139], v[112:127]
	v_mfma_f32_32x32x16_bf16 v[80:95], v[184:187], v[156:159], v[80:95]
	ds_read_b128 v[184:187], v176 offset:6688
	s_waitcnt lgkmcnt(11)
	v_mfma_f32_32x32x16_bf16 v[112:127], v[188:191], v[140:143], v[112:127]
	v_mfma_f32_32x32x16_bf16 v[80:95], v[188:191], v[160:163], v[80:95]
	ds_read_b128 v[188:191], v176 offset:6720
	s_waitcnt lgkmcnt(11)
	v_mfma_f32_32x32x16_bf16 v[112:127], v[192:195], v[144:147], v[112:127]
	v_mfma_f32_32x32x16_bf16 v[80:95], v[192:195], v[164:167], v[80:95]
	ds_read_b128 v[192:195], v176 offset:6752
	s_waitcnt lgkmcnt(3)
	v_mfma_f32_32x32x16_bf16 v[96:111], v[180:183], v[132:135], 0
	v_mfma_f32_32x32x16_bf16 v[64:79], v[180:183], v[152:155], 0
	ds_read2_b32 v[222:223], v251 offset0:0 offset1:1
	ds_read2_b32 v[224:225], v251 offset0:2 offset1:3
	ds_read2_b32 v[226:227], v251 offset0:8 offset1:9
	ds_read2_b32 v[228:229], v251 offset0:10 offset1:11
	ds_read2_b32 v[230:231], v251 offset0:16 offset1:17
	ds_read2_b32 v[232:233], v251 offset0:18 offset1:19
	ds_read2_b32 v[238:239], v251 offset0:24 offset1:25
	ds_read2_b32 v[240:241], v251 offset0:26 offset1:27
	v_fmamk_f32 v112, v112, 0x3e38aa3b, v206
	v_fmamk_f32 v113, v113, 0x3e38aa3b, v207
	v_fmamk_f32 v114, v114, 0x3e38aa3b, v208
	v_fmamk_f32 v115, v115, 0x3e38aa3b, v209
	v_fmamk_f32 v116, v116, 0x3e38aa3b, v210
	v_fmamk_f32 v117, v117, 0x3e38aa3b, v211
	s_waitcnt lgkmcnt(10)
	v_mfma_f32_32x32x16_bf16 v[96:111], v[184:187], v[136:139], v[96:111]
	v_mfma_f32_32x32x16_bf16 v[64:79], v[184:187], v[156:159], v[64:79]
	v_fmamk_f32 v118, v118, 0x3e38aa3b, v212
	v_fmamk_f32 v119, v119, 0x3e38aa3b, v213
	v_fmamk_f32 v120, v120, 0x3e38aa3b, v214
	v_fmamk_f32 v121, v121, 0x3e38aa3b, v215
	v_fmamk_f32 v122, v122, 0x3e38aa3b, v216
	v_fmamk_f32 v123, v123, 0x3e38aa3b, v217
	v_fmamk_f32 v124, v124, 0x3e38aa3b, v218
	v_fmamk_f32 v125, v125, 0x3e38aa3b, v219
	s_waitcnt lgkmcnt(9)
	v_mfma_f32_32x32x16_bf16 v[96:111], v[188:191], v[140:143], v[96:111]
	v_mfma_f32_32x32x16_bf16 v[64:79], v[188:191], v[160:163], v[64:79]
	v_fmamk_f32 v126, v126, 0x3e38aa3b, v220
	v_fmamk_f32 v127, v127, 0x3e38aa3b, v221
	v_max3_f32 v234, v112, v113, v114
	v_max3_f32 v234, v234, v115, v116
	v_max3_f32 v234, v234, v117, v118
	v_max3_f32 v234, v234, v119, v120
	v_max3_f32 v234, v234, v121, v122
	v_max3_f32 v234, v234, v123, v124
	s_waitcnt lgkmcnt(8)
	v_mfma_f32_32x32x16_bf16 v[96:111], v[192:195], v[144:147], v[96:111]
	v_mfma_f32_32x32x16_bf16 v[64:79], v[192:195], v[164:167], v[64:79]
	v_max3_f32 v234, v234, v125, v126
	v_max_f32_e32 v234, v234, v127
	s_waitcnt lgkmcnt(0)
	ds_read2_b32 v[180:181], v251 offset0:64 offset1:65
	ds_read2_b32 v[182:183], v251 offset0:66 offset1:67
	ds_read2_b32 v[184:185], v251 offset0:72 offset1:73
	ds_read2_b32 v[186:187], v251 offset0:74 offset1:75
	ds_read2_b32 v[188:189], v251 offset0:80 offset1:81
	ds_read2_b32 v[190:191], v251 offset0:82 offset1:83
	ds_read2_b32 v[192:193], v251 offset0:88 offset1:89
	ds_read2_b32 v[194:195], v251 offset0:90 offset1:91
	v_fmamk_f32 v80, v80, 0x3e38aa3b, v222
	v_fmamk_f32 v81, v81, 0x3e38aa3b, v223
	v_fmamk_f32 v82, v82, 0x3e38aa3b, v224
	v_fmamk_f32 v83, v83, 0x3e38aa3b, v225
	v_fmamk_f32 v84, v84, 0x3e38aa3b, v226
	v_fmamk_f32 v85, v85, 0x3e38aa3b, v227
	v_fmamk_f32 v86, v86, 0x3e38aa3b, v228
	v_fmamk_f32 v87, v87, 0x3e38aa3b, v229
	v_fmamk_f32 v88, v88, 0x3e38aa3b, v230
	v_fmamk_f32 v89, v89, 0x3e38aa3b, v231
	v_fmamk_f32 v90, v90, 0x3e38aa3b, v232
	v_fmamk_f32 v91, v91, 0x3e38aa3b, v233
	v_fmamk_f32 v92, v92, 0x3e38aa3b, v238
	v_fmamk_f32 v93, v93, 0x3e38aa3b, v239
	v_fmamk_f32 v94, v94, 0x3e38aa3b, v240
	v_fmamk_f32 v95, v95, 0x3e38aa3b, v241
	v_max3_f32 v235, v80, v81, v82
	v_max3_f32 v235, v235, v83, v84
	v_max3_f32 v235, v235, v85, v86
	v_max3_f32 v235, v235, v87, v88
	v_max3_f32 v235, v235, v89, v90
	v_max3_f32 v235, v235, v91, v92
	v_max3_f32 v235, v235, v93, v94
	v_max_f32_e32 v235, v235, v95
	v_fmamk_f32 v64, v64, 0x3e38aa3b, v206
	v_fmamk_f32 v65, v65, 0x3e38aa3b, v207
	v_fmamk_f32 v66, v66, 0x3e38aa3b, v208
	v_fmamk_f32 v67, v67, 0x3e38aa3b, v209
	v_fmamk_f32 v68, v68, 0x3e38aa3b, v210
	v_fmamk_f32 v69, v69, 0x3e38aa3b, v211
	v_fmamk_f32 v70, v70, 0x3e38aa3b, v212
	v_fmamk_f32 v71, v71, 0x3e38aa3b, v213
	v_fmamk_f32 v72, v72, 0x3e38aa3b, v214
	v_fmamk_f32 v73, v73, 0x3e38aa3b, v215
	v_fmamk_f32 v74, v74, 0x3e38aa3b, v216
	v_fmamk_f32 v75, v75, 0x3e38aa3b, v217
	v_fmamk_f32 v76, v76, 0x3e38aa3b, v218
	v_fmamk_f32 v77, v77, 0x3e38aa3b, v219
	v_fmamk_f32 v78, v78, 0x3e38aa3b, v220
	v_fmamk_f32 v79, v79, 0x3e38aa3b, v221
	v_max3_f32 v235, v235, v64, v65
	v_max3_f32 v235, v235, v66, v67
	v_max3_f32 v235, v235, v68, v69
	v_max3_f32 v235, v235, v70, v71
	v_max3_f32 v235, v235, v72, v73
	v_max3_f32 v235, v235, v74, v75
	v_max3_f32 v235, v235, v76, v77
	v_max3_f32 v235, v235, v78, v79
	ds_bpermute_b32 v199, v173, v235
	s_waitcnt lgkmcnt(1)
; __device__ __forceinline__ float shx(float v, int lane, int o) { return __builtin_bit_cast(float, __builtin_amdgcn_ds_bpermute((lane ^ o) << 2, __builtin_bit_cast(int, v))); }
; __device__ __forceinline__ int crow(int i, int hi) { return (i & 3) + 8 * (i >> 2) + 4 * hi; }
; template <int DQ, bool BIAS>
; __device__ __forceinline__ void attn_item_l0(const AttnItem& A, LAS unsigned char* lds, int wave_s_) {
;     ...
;             for (int qb = 0; qb < 2; ++qb) {
;                 const int qk = A.q_kidx0 + 64 * w + 32 * qb + r32;
;                 float mx = -3.0e38f;
; #pragma unroll
;                 for (int kbk = 0; kbk < 2; ++kbk)
; #pragma unroll
;                     for (int i = 0; i < 16; ++i) {
;                         const int kidx = 64 * t + 32 * kbk + crow(i, hi);
;                         float v = s[kbk][qb][i] * A.scale2;
;                         if (BIAS) v += lut[kidx - qk + LUT0];
;                         if (kidx >= A.nkeys) v = -1.0e30f;
;                         s[kbk][qb][i] = v; mx = fmaxf(mx, v);
;                     }
;                 mx = fmaxf(mx, shx(mx, lane, 32));
;                 const float mnew = fmaxf(mrun[qb], mx), alpha = __builtin_amdgcn_exp2f(mrun[qb] - mnew);
;                 mrun[qb] = mnew;
;                 float ls = 0.f;
; #pragma unroll
;                 for (int kbk = 0; kbk < 2; ++kbk)
; #pragma unroll
;                     for (int i = 0; i < 16; ++i) { const float p = __builtin_amdgcn_exp2f(s[kbk][qb][i] - mnew); s[kbk][qb][i] = p; ls += p; }
;                 lrun[qb] = lrun[qb] * alpha + ls;
; #pragma unroll
;                 for (int d = 0; d < 2; ++d)
; #pragma unroll
;                     for (int i = 0; i < 16; ++i) o[d][qb][i] *= alpha;
	v_fmamk_f32 v96, v96, 0x3e38aa3b, v180
	v_fmamk_f32 v97, v97, 0x3e38aa3b, v181
	v_fmamk_f32 v98, v98, 0x3e38aa3b, v182
	v_fmamk_f32 v99, v99, 0x3e38aa3b, v183
	v_fmamk_f32 v100, v100, 0x3e38aa3b, v184
	v_fmamk_f32 v101, v101, 0x3e38aa3b, v185
	v_fmamk_f32 v102, v102, 0x3e38aa3b, v186
	v_fmamk_f32 v103, v103, 0x3e38aa3b, v187
	v_fmamk_f32 v104, v104, 0x3e38aa3b, v188
	v_fmamk_f32 v105, v105, 0x3e38aa3b, v189
	v_fmamk_f32 v106, v106, 0x3e38aa3b, v190
	v_fmamk_f32 v107, v107, 0x3e38aa3b, v191
	v_fmamk_f32 v108, v108, 0x3e38aa3b, v192
	v_fmamk_f32 v109, v109, 0x3e38aa3b, v193
	v_fmamk_f32 v110, v110, 0x3e38aa3b, v194
	v_fmamk_f32 v111, v111, 0x3e38aa3b, v195
	v_max3_f32 v234, v234, v96, v97
	v_max3_f32 v234, v234, v98, v99
	v_max3_f32 v234, v234, v100, v101
	v_max3_f32 v234, v234, v102, v103
	v_max3_f32 v234, v234, v104, v105
	v_max3_f32 v234, v234, v106, v107
	v_max3_f32 v234, v234, v108, v109
	v_max3_f32 v234, v234, v110, v111
	ds_bpermute_b32 v198, v173, v234
	ds_read2_b64 v[206:209], v244 offset0:0 offset1:2
	ds_read2_b64 v[210:213], v253 offset0:32 offset1:34
	ds_read2_b64 v[214:217], v244 offset0:4 offset1:6
	ds_read2_b64 v[218:221], v253 offset0:36 offset1:38
	ds_read2_b64 v[222:225], v244 offset0:8 offset1:10
	ds_read2_b64 v[226:229], v253 offset0:40 offset1:42
	ds_read2_b64 v[230:233], v244 offset0:12 offset1:14
	ds_read2_b64 v[180:183], v253 offset0:44 offset1:46
	s_waitcnt lgkmcnt(9)
	v_max3_f32 v205, v179, v235, v199
	v_sub_f32_e32 v177, v179, v205
	v_exp_f32_e32 v177, v177
	v_mov_b32_e32 v179, v205
	v_sub_f32_e32 v80, v80, v205
	v_sub_f32_e32 v81, v81, v205
	v_sub_f32_e32 v82, v82, v205
	v_sub_f32_e32 v83, v83, v205
	v_exp_f32_e32 v80, v80
	v_exp_f32_e32 v81, v81
	v_exp_f32_e32 v82, v82
	v_exp_f32_e32 v83, v83
	v_sub_f32_e32 v84, v84, v205
	v_sub_f32_e32 v85, v85, v205
	v_sub_f32_e32 v86, v86, v205
	v_sub_f32_e32 v87, v87, v205
	v_exp_f32_e32 v84, v84
	v_exp_f32_e32 v85, v85
	v_exp_f32_e32 v86, v86
	v_exp_f32_e32 v87, v87
	v_add_f32_e32 v235, v80, v81
	v_add_f32_e32 v235, v235, v82
	v_add_f32_e32 v235, v235, v83
	v_sub_f32_e32 v88, v88, v205
	v_sub_f32_e32 v89, v89, v205
	v_sub_f32_e32 v90, v90, v205
	v_sub_f32_e32 v91, v91, v205
	v_exp_f32_e32 v88, v88
	v_exp_f32_e32 v89, v89
	v_exp_f32_e32 v90, v90
	v_exp_f32_e32 v91, v91
	v_add_f32_e32 v235, v235, v84
	v_add_f32_e32 v235, v235, v85
	v_add_f32_e32 v235, v235, v86
	v_add_f32_e32 v235, v235, v87
	v_sub_f32_e32 v92, v92, v205
	v_sub_f32_e32 v93, v93, v205
	v_sub_f32_e32 v94, v94, v205
	v_sub_f32_e32 v95, v95, v205
	v_exp_f32_e32 v92, v92
	v_exp_f32_e32 v93, v93
	v_exp_f32_e32 v94, v94
	v_exp_f32_e32 v95, v95
	v_add_f32_e32 v235, v235, v88
	v_add_f32_e32 v235, v235, v89
	v_add_f32_e32 v235, v235, v90
	v_add_f32_e32 v235, v235, v91
	v_add_f32_e32 v235, v235, v92
	v_add_f32_e32 v235, v235, v93
	v_add_f32_e32 v235, v235, v94
	v_add_f32_e32 v235, v235, v95
	v_sub_f32_e32 v64, v64, v205
	v_sub_f32_e32 v65, v65, v205
	v_sub_f32_e32 v66, v66, v205
	v_sub_f32_e32 v67, v67, v205
	v_exp_f32_e32 v64, v64
	v_exp_f32_e32 v65, v65
	v_exp_f32_e32 v66, v66
	v_exp_f32_e32 v67, v67
	v_sub_f32_e32 v68, v68, v205
	v_sub_f32_e32 v69, v69, v205
	v_sub_f32_e32 v70, v70, v205
	v_sub_f32_e32 v71, v71, v205
	v_exp_f32_e32 v68, v68
	v_exp_f32_e32 v69, v69
	v_exp_f32_e32 v70, v70
	v_exp_f32_e32 v71, v71
	v_add_f32_e32 v235, v235, v64
	v_add_f32_e32 v235, v235, v65
	v_add_f32_e32 v235, v235, v66
	v_add_f32_e32 v235, v235, v67
	v_sub_f32_e32 v72, v72, v205
	v_sub_f32_e32 v73, v73, v205
	v_sub_f32_e32 v74, v74, v205
	v_sub_f32_e32 v75, v75, v205
	v_exp_f32_e32 v72, v72
	v_exp_f32_e32 v73, v73
	v_exp_f32_e32 v74, v74
	v_exp_f32_e32 v75, v75
	v_add_f32_e32 v235, v235, v68
	v_add_f32_e32 v235, v235, v69
	v_add_f32_e32 v235, v235, v70
	v_add_f32_e32 v235, v235, v71
	v_sub_f32_e32 v76, v76, v205
	v_sub_f32_e32 v77, v77, v205
	v_sub_f32_e32 v78, v78, v205
	v_sub_f32_e32 v79, v79, v205
	v_exp_f32_e32 v76, v76
	v_exp_f32_e32 v77, v77
	v_exp_f32_e32 v78, v78
	v_exp_f32_e32 v79, v79
	v_add_f32_e32 v235, v235, v72
	v_add_f32_e32 v235, v235, v73
	v_add_f32_e32 v235, v235, v74
	v_add_f32_e32 v235, v235, v75
	v_add_f32_e32 v235, v235, v76
	v_add_f32_e32 v235, v235, v77
	v_add_f32_e32 v235, v235, v78
	v_add_f32_e32 v235, v235, v79
	v_fma_f32 v169, v169, v177, v235
	s_waitcnt lgkmcnt(8)
; __device__ __forceinline__ unsigned pk2c(float lo, float hi) { f32x2_t v = {lo, hi}; bf16x2_t b = __builtin_convertvector(v, bf16x2_t); return __builtin_bit_cast(unsigned, b); }
; __device__ __forceinline__ float shx(float v, int lane, int o) { return __builtin_bit_cast(float, __builtin_amdgcn_ds_bpermute((lane ^ o) << 2, __builtin_bit_cast(int, v))); }
; template <int DQ, bool BIAS>
; __device__ __forceinline__ void attn_item_l0(const AttnItem& A, LAS unsigned char* lds, int wave_s_) {
;     ...
;                 mx = fmaxf(mx, shx(mx, lane, 32));
;                 const float mnew = fmaxf(mrun[qb], mx), alpha = __builtin_amdgcn_exp2f(mrun[qb] - mnew);
;                 mrun[qb] = mnew;
;                 float ls = 0.f;
; #pragma unroll
;                 for (int kbk = 0; kbk < 2; ++kbk)
; #pragma unroll
;                     for (int i = 0; i < 16; ++i) { const float p = __builtin_amdgcn_exp2f(s[kbk][qb][i] - mnew); s[kbk][qb][i] = p; ls += p; }
;                 lrun[qb] = lrun[qb] * alpha + ls;
; #pragma unroll
;                 for (int d = 0; d < 2; ++d)
; #pragma unroll
;                     for (int i = 0; i < 16; ++i) o[d][qb][i] *= alpha;
;             }
; #pragma unroll
;             for (int kbk = 0; kbk < 2; ++kbk)
; #pragma unroll
;                 for (int st = 0; st < 2; ++st) {
;                     bf16x8 pf[2];
; #pragma unroll
;                     for (int qb = 0; qb < 2; ++qb) { u32x4 pw;
; #pragma unroll
;                         for (int j = 0; j < 4; ++j) pw[j] = pk2c(s[kbk][qb][8 * st + 2 * j], s[kbk][qb][8 * st + 2 * j + 1]);
;                         pf[qb] = __builtin_bit_cast(bf16x8, pw); }
	v_max3_f32 v204, v178, v234, v198
	v_sub_f32_e32 v176, v178, v204
	v_exp_f32_e32 v176, v176
	v_mov_b32_e32 v178, v204
	v_sub_f32_e32 v112, v112, v204
	v_sub_f32_e32 v113, v113, v204
	v_sub_f32_e32 v114, v114, v204
	v_sub_f32_e32 v115, v115, v204
	v_exp_f32_e32 v112, v112
	v_exp_f32_e32 v113, v113
	v_exp_f32_e32 v114, v114
	v_exp_f32_e32 v115, v115
	v_sub_f32_e32 v116, v116, v204
	v_sub_f32_e32 v117, v117, v204
	v_sub_f32_e32 v118, v118, v204
	v_sub_f32_e32 v119, v119, v204
	v_exp_f32_e32 v116, v116
	v_exp_f32_e32 v117, v117
	v_exp_f32_e32 v118, v118
	v_exp_f32_e32 v119, v119
	v_add_f32_e32 v196, v112, v113
	v_add_f32_e32 v196, v196, v114
	v_add_f32_e32 v196, v196, v115
	v_sub_f32_e32 v120, v120, v204
	v_sub_f32_e32 v121, v121, v204
	v_sub_f32_e32 v122, v122, v204
	v_sub_f32_e32 v123, v123, v204
	v_exp_f32_e32 v120, v120
	v_exp_f32_e32 v121, v121
	v_exp_f32_e32 v122, v122
	v_exp_f32_e32 v123, v123
	v_add_f32_e32 v196, v196, v116
	v_add_f32_e32 v196, v196, v117
	v_add_f32_e32 v196, v196, v118
	v_add_f32_e32 v196, v196, v119
	v_sub_f32_e32 v124, v124, v204
	v_sub_f32_e32 v125, v125, v204
	v_sub_f32_e32 v126, v126, v204
	v_sub_f32_e32 v127, v127, v204
	v_exp_f32_e32 v124, v124
	v_exp_f32_e32 v125, v125
	v_exp_f32_e32 v126, v126
	v_exp_f32_e32 v127, v127
	v_add_f32_e32 v196, v196, v120
	v_add_f32_e32 v196, v196, v121
	v_add_f32_e32 v196, v196, v122
	v_add_f32_e32 v196, v196, v123
	v_add_f32_e32 v196, v196, v124
	v_add_f32_e32 v196, v196, v125
	v_add_f32_e32 v196, v196, v126
	v_add_f32_e32 v196, v196, v127
	v_sub_f32_e32 v96, v96, v204
	v_sub_f32_e32 v97, v97, v204
	v_sub_f32_e32 v98, v98, v204
	v_sub_f32_e32 v99, v99, v204
	v_exp_f32_e32 v96, v96
	v_exp_f32_e32 v97, v97
	v_exp_f32_e32 v98, v98
	v_exp_f32_e32 v99, v99
	v_sub_f32_e32 v100, v100, v204
	v_sub_f32_e32 v101, v101, v204
	v_sub_f32_e32 v102, v102, v204
	v_sub_f32_e32 v103, v103, v204
	v_exp_f32_e32 v100, v100
	v_exp_f32_e32 v101, v101
	v_exp_f32_e32 v102, v102
	v_exp_f32_e32 v103, v103
	v_add_f32_e32 v196, v196, v96
	v_add_f32_e32 v196, v196, v97
	v_add_f32_e32 v196, v196, v98
	v_add_f32_e32 v196, v196, v99
	v_sub_f32_e32 v104, v104, v204
	v_sub_f32_e32 v105, v105, v204
	v_sub_f32_e32 v106, v106, v204
	v_sub_f32_e32 v107, v107, v204
	v_exp_f32_e32 v104, v104
	v_exp_f32_e32 v105, v105
	v_exp_f32_e32 v106, v106
	v_exp_f32_e32 v107, v107
	v_add_f32_e32 v196, v196, v100
	v_add_f32_e32 v196, v196, v101
	v_add_f32_e32 v196, v196, v102
	v_add_f32_e32 v196, v196, v103
	v_sub_f32_e32 v108, v108, v204
	v_sub_f32_e32 v109, v109, v204
	v_sub_f32_e32 v110, v110, v204
	v_sub_f32_e32 v111, v111, v204
	v_exp_f32_e32 v108, v108
	v_exp_f32_e32 v109, v109
	v_exp_f32_e32 v110, v110
	v_exp_f32_e32 v111, v111
	v_add_f32_e32 v196, v196, v104
	v_add_f32_e32 v196, v196, v105
	v_add_f32_e32 v196, v196, v106
	v_add_f32_e32 v196, v196, v107
	v_add_f32_e32 v196, v196, v108
	v_add_f32_e32 v196, v196, v109
	v_add_f32_e32 v196, v196, v110
	v_add_f32_e32 v196, v196, v111
	v_fma_f32 v168, v168, v176, v196
	v_mul_f32_e32 v16, v16, v177
	v_mul_f32_e32 v17, v17, v177
	v_mul_f32_e32 v18, v18, v177
	v_mul_f32_e32 v19, v19, v177
	v_mul_f32_e32 v20, v20, v177
	v_mul_f32_e32 v21, v21, v177
	v_mul_f32_e32 v22, v22, v177
	v_mul_f32_e32 v23, v23, v177
	v_mul_f32_e32 v24, v24, v177
	v_mul_f32_e32 v25, v25, v177
	v_mul_f32_e32 v26, v26, v177
	v_mul_f32_e32 v27, v27, v177
	v_mul_f32_e32 v28, v28, v177
	v_mul_f32_e32 v29, v29, v177
	v_mul_f32_e32 v30, v30, v177
	v_mul_f32_e32 v31, v31, v177
	v_mul_f32_e32 v0, v0, v177
	v_mul_f32_e32 v1, v1, v177
	v_mul_f32_e32 v2, v2, v177
	v_mul_f32_e32 v3, v3, v177
	v_mul_f32_e32 v4, v4, v177
	v_mul_f32_e32 v5, v5, v177
	v_mul_f32_e32 v6, v6, v177
	v_mul_f32_e32 v7, v7, v177
	v_mul_f32_e32 v8, v8, v177
	v_mul_f32_e32 v9, v9, v177
	v_mul_f32_e32 v10, v10, v177
	v_mul_f32_e32 v11, v11, v177
	v_mul_f32_e32 v12, v12, v177
	v_mul_f32_e32 v13, v13, v177
	v_mul_f32_e32 v14, v14, v177
	v_mul_f32_e32 v15, v15, v177
	v_cvt_pk_bf16_f32 v80, v80, v81
	v_cvt_pk_bf16_f32 v81, v82, v83
	v_cvt_pk_bf16_f32 v82, v84, v85
	v_cvt_pk_bf16_f32 v83, v86, v87
	v_cvt_pk_bf16_f32 v84, v88, v89
	v_cvt_pk_bf16_f32 v85, v90, v91
	v_cvt_pk_bf16_f32 v86, v92, v93
	v_cvt_pk_bf16_f32 v87, v94, v95
	v_cvt_pk_bf16_f32 v64, v64, v65
	v_cvt_pk_bf16_f32 v65, v66, v67
	v_cvt_pk_bf16_f32 v66, v68, v69
	v_cvt_pk_bf16_f32 v67, v70, v71
	v_cvt_pk_bf16_f32 v68, v72, v73
	v_cvt_pk_bf16_f32 v69, v74, v75
	v_cvt_pk_bf16_f32 v70, v76, v77
	v_cvt_pk_bf16_f32 v71, v78, v79
	v_mul_f32_e32 v32, v32, v176
	v_mul_f32_e32 v33, v33, v176
	v_mul_f32_e32 v34, v34, v176
	s_waitcnt lgkmcnt(7)
; #define LAS __attribute__((address_space(3)))
; __device__ __forceinline__ unsigned pk2c(float lo, float hi) { f32x2_t v = {lo, hi}; bf16x2_t b = __builtin_convertvector(v, bf16x2_t); return __builtin_bit_cast(unsigned, b); }
; #define MFMA32(a, b, c) __builtin_amdgcn_mfma_f32_32x32x16_bf16((a), (b), (c), 0, 0, 0)
; template <int DQ, bool BIAS>
; __device__ __forceinline__ void attn_item_l0(const AttnItem& A, LAS unsigned char* lds, int wave_s_) {
;     ...
; #pragma unroll
;             for (int kbk = 0; kbk < 2; ++kbk)
; #pragma unroll
;                 for (int st = 0; st < 2; ++st) {
;                     bf16x8 pf[2];
; #pragma unroll
;                     for (int qb = 0; qb < 2; ++qb) { u32x4 pw;
; #pragma unroll
;                         for (int j = 0; j < 4; ++j) pw[j] = pk2c(s[kbk][qb][8 * st + 2 * j], s[kbk][qb][8 * st + 2 * j + 1]);
;                         pf[qb] = __builtin_bit_cast(bf16x8, pw); }
; #pragma unroll
;                     for (int d = 0; d < 2; ++d) {
;                         const LAS unsigned char* vp = vb + ((32 * d + r32) * OVSTR + 32 * kbk + 16 * st + 4 * hi) * 2;
;                         const s16x4 lo4 = *(const LAS s16x4*)vp, hi4 = *(const LAS s16x4*)(vp + 16);
;                         const bf16x8 vf = __builtin_shufflevector(lo4, hi4, 0, 1, 2, 3, 4, 5, 6, 7);
;                         o[d][0] = MFMA32(vf, pf[0], o[d][0]);
;                         o[d][1] = MFMA32(vf, pf[1], o[d][1]);
;                     }
;                 }
	v_mfma_f32_32x32x16_bf16 v[16:31], v[206:209], v[80:83], v[16:31]
	v_mul_f32_e32 v35, v35, v176
	v_mul_f32_e32 v36, v36, v176
	v_mul_f32_e32 v37, v37, v176
	v_mul_f32_e32 v38, v38, v176
	v_mul_f32_e32 v39, v39, v176
	s_waitcnt lgkmcnt(6)
	v_mfma_f32_32x32x16_bf16 v[0:15], v[210:213], v[80:83], v[0:15]
	v_mul_f32_e32 v40, v40, v176
	v_mul_f32_e32 v41, v41, v176
	v_mul_f32_e32 v42, v42, v176
	v_mul_f32_e32 v43, v43, v176
	v_mul_f32_e32 v44, v44, v176
	s_waitcnt lgkmcnt(5)
	v_mfma_f32_32x32x16_bf16 v[16:31], v[214:217], v[84:87], v[16:31]
	v_mul_f32_e32 v45, v45, v176
	v_mul_f32_e32 v46, v46, v176
	v_mul_f32_e32 v47, v47, v176
	v_mul_f32_e32 v48, v48, v176
	v_mul_f32_e32 v49, v49, v176
	s_waitcnt lgkmcnt(4)
	v_mfma_f32_32x32x16_bf16 v[0:15], v[218:221], v[84:87], v[0:15]
	v_mul_f32_e32 v50, v50, v176
	v_mul_f32_e32 v51, v51, v176
	v_mul_f32_e32 v52, v52, v176
	v_mul_f32_e32 v53, v53, v176
	v_mul_f32_e32 v54, v54, v176
	s_waitcnt lgkmcnt(3)
	v_mfma_f32_32x32x16_bf16 v[16:31], v[222:225], v[64:67], v[16:31]
	v_mul_f32_e32 v55, v55, v176
	v_mul_f32_e32 v56, v56, v176
	v_mul_f32_e32 v57, v57, v176
	v_mul_f32_e32 v58, v58, v176
	v_mul_f32_e32 v59, v59, v176
	s_waitcnt lgkmcnt(2)
	v_mfma_f32_32x32x16_bf16 v[0:15], v[226:229], v[64:67], v[0:15]
	v_mul_f32_e32 v60, v60, v176
	v_mul_f32_e32 v61, v61, v176
	v_mul_f32_e32 v62, v62, v176
	v_mul_f32_e32 v63, v63, v176
	v_cvt_pk_bf16_f32 v112, v112, v113
	s_waitcnt lgkmcnt(1)
	v_mfma_f32_32x32x16_bf16 v[16:31], v[230:233], v[68:71], v[16:31]
	v_cvt_pk_bf16_f32 v113, v114, v115
	v_cvt_pk_bf16_f32 v114, v116, v117
	v_cvt_pk_bf16_f32 v115, v118, v119
	v_cvt_pk_bf16_f32 v116, v120, v121
	v_cvt_pk_bf16_f32 v117, v122, v123
	s_waitcnt lgkmcnt(0)
	v_mfma_f32_32x32x16_bf16 v[0:15], v[180:183], v[68:71], v[0:15]
	v_cvt_pk_bf16_f32 v118, v124, v125
	v_cvt_pk_bf16_f32 v119, v126, v127
	v_cvt_pk_bf16_f32 v96, v96, v97
	v_cvt_pk_bf16_f32 v97, v98, v99
	v_cvt_pk_bf16_f32 v98, v100, v101
	v_cvt_pk_bf16_f32 v99, v102, v103
	v_cvt_pk_bf16_f32 v100, v104, v105
	v_cvt_pk_bf16_f32 v101, v106, v107
	v_cvt_pk_bf16_f32 v102, v108, v109
	v_cvt_pk_bf16_f32 v103, v110, v111
	s_nop 1
	v_mfma_f32_32x32x16_bf16 v[32:47], v[206:209], v[112:115], v[32:47]
	v_mfma_f32_32x32x16_bf16 v[48:63], v[210:213], v[112:115], v[48:63]
	v_mfma_f32_32x32x16_bf16 v[32:47], v[214:217], v[116:119], v[32:47]
	v_mfma_f32_32x32x16_bf16 v[48:63], v[218:221], v[116:119], v[48:63]
	v_mfma_f32_32x32x16_bf16 v[32:47], v[222:225], v[96:99], v[32:47]
	v_mfma_f32_32x32x16_bf16 v[48:63], v[226:229], v[96:99], v[48:63]
	v_mfma_f32_32x32x16_bf16 v[32:47], v[230:233], v[100:103], v[32:47]
	v_mfma_f32_32x32x16_bf16 v[48:63], v[180:183], v[100:103], v[48:63]
